# baseline (speedup 1.0000x reference)
; __device__ __forceinline__ float bf2f(u16 v) { return __uint_as_float(((uint32_t)v) << 16); }
; __device__ __forceinline__ uint2 pack4(float a, float b, float c, float d) { return make_uint2(pack2(a, b), pack2(c, d)); }
; __global__ void __launch_bounds__(NTHREADS, 2) fwd_megakernel(Params p_arg) {
;     ...
;         for (int tt = 0; tt < 8; ++tt) {
;           bf16x8 wf[4];
; #pragma unroll
;           for (int ks = 0; ks < 4; ++ks) wf[ks] = *(const bf16x8*)(wsb + (tt * 16 + fr) * 128 + ks * 32 + fq * 8);
;           f32x4 ac[4];
; #pragma unroll
;           for (int ct = 0; ct < 4; ++ct) ac[ct] = f32x4{0.f, 0.f, 0.f, 0.f};
; #pragma unroll
;           for (int ks = 0; ks < 4; ++ks)
; #pragma unroll
;             for (int ct = 0; ct < 4; ++ct) ac[ct] = __builtin_amdgcn_mfma_f32_16x16x32_bf16(vf[ct][ks], wf[ks], ac[ct], 0, 0, 0);
;           const size_t tok = tok0 + tt * 16 + fr;
;           const float bias = pk->gm_b_s[((size_t)l * 8 + g) * 128 + tt * 16 + fr];
; #pragma unroll
;           for (int cp = 0; cp < 2; ++cp) {
;             uint2 ur[2], ov[2];
;             load_pair16(ZUp + tok * 512 + g * 64 + cp * 32, fq, ur[0], ur[1]);
; #pragma unroll
;             for (int q = 0; q < 2; ++q) {
;               const int ct = cp * 2 + q;
;               float u0 = bf2f((u16)(ur[q].x & 0xffffu)), u1 = bf2f((u16)(ur[q].x >> 16)), u2 = bf2f((u16)(ur[q].y & 0xffffu)), u3 = bf2f((u16)(ur[q].y >> 16));
;               ov[q] = pack4(u0 * (ac[ct][0] + bias), u1 * (ac[ct][1] + bias), u2 * (ac[ct][2] + bias), u3 * (ac[ct][3] + bias));
;             }
;             store_pair16(ABp + tok * 1024 + g * 64 + cp * 32, fq, ov[0], ov[1]);
;           }
;         }
.LBB0_297:
	global_load_dwordx4 v[102:105], v[70:71], off offset:-128
	global_load_dwordx4 v[106:109], v[70:71], off offset:-64
	global_load_dwordx4 v[154:157], v[70:71], off
	global_load_dwordx4 v[158:161], v[70:71], off offset:64
	v_lshl_add_u64 v[72:73], v[88:89], 0, s[10:11]
	global_load_dword v0, v[72:73], off
	v_lshl_add_u64 v[72:73], v[66:67], 0, s[34:35]
	global_load_dwordx4 v[192:195], v[72:73], off
	global_load_dwordx4 v[196:199], v[72:73], off offset:64
	v_lshl_add_u64 v[110:111], v[68:69], 0, s[34:35]
	s_add_u32 s10, s10, 64
	s_addc_u32 s11, s11, 0
	s_mov_b64 s[12:13], 0x8000
	v_lshl_add_u64 v[70:71], v[70:71], 0, s[48:49]
	v_lshl_add_u64 v[66:67], v[66:67], 0, s[94:95]
	v_lshl_add_u64 v[68:69], v[68:69], 0, s[12:13]
	s_cmpk_eq_i32 s10, 0x200
	s_waitcnt vmcnt(6) lgkmcnt(14)
	v_mfma_f32_16x16x32_bf16 v[180:183], v[2:5], v[102:105], 0
	s_waitcnt lgkmcnt(11)
	v_mfma_f32_16x16x32_bf16 v[184:187], v[18:21], v[102:105], 0
	s_waitcnt lgkmcnt(7)
	v_mfma_f32_16x16x32_bf16 v[188:191], v[34:37], v[102:105], 0
	s_waitcnt lgkmcnt(3)
	v_mfma_f32_16x16x32_bf16 v[102:105], v[50:53], v[102:105], 0
	s_waitcnt vmcnt(5)
	v_mfma_f32_16x16x32_bf16 v[180:183], v[6:9], v[106:109], v[180:183]
	v_mfma_f32_16x16x32_bf16 v[184:187], v[22:25], v[106:109], v[184:187]
	v_mfma_f32_16x16x32_bf16 v[188:191], v[38:41], v[106:109], v[188:191]
	s_waitcnt lgkmcnt(2)
	v_mfma_f32_16x16x32_bf16 v[102:105], v[54:57], v[106:109], v[102:105]
	s_waitcnt vmcnt(4)
	v_mfma_f32_16x16x32_bf16 v[106:109], v[10:13], v[154:157], v[180:183]
	v_mfma_f32_16x16x32_bf16 v[180:183], v[26:29], v[154:157], v[184:187]
	v_mfma_f32_16x16x32_bf16 v[184:187], v[42:45], v[154:157], v[188:191]
	s_waitcnt lgkmcnt(1)
	v_mfma_f32_16x16x32_bf16 v[102:105], v[58:61], v[154:157], v[102:105]
	s_waitcnt vmcnt(3)
	v_mfma_f32_16x16x32_bf16 v[106:109], v[14:17], v[158:161], v[106:109]
	v_mfma_f32_16x16x32_bf16 v[154:157], v[30:33], v[158:161], v[180:183]
	v_mfma_f32_16x16x32_bf16 v[180:183], v[46:49], v[158:161], v[184:187]
	s_waitcnt vmcnt(2)
	s_nop 4
	v_pk_add_f32 v[106:107], v[0:1], v[106:107] op_sel_hi:[0,1]
	v_pk_add_f32 v[108:109], v[0:1], v[108:109] op_sel_hi:[0,1]
	v_pk_add_f32 v[154:155], v[0:1], v[154:155] op_sel_hi:[0,1]
	s_waitcnt lgkmcnt(0)
	v_mfma_f32_16x16x32_bf16 v[102:105], v[62:65], v[158:161], v[102:105]
	s_waitcnt vmcnt(1)
	v_mov_b32_e32 v101, v194
	v_mov_b32_e32 v151, v195
	s_nop 0
	v_permlane16_swap_b32_e32 v192, v101
	v_permlane16_swap_b32_e32 v193, v151
	v_lshlrev_b32_e32 v160, 16, v192
	v_and_b32_e32 v161, 0xffff0000, v192
	v_lshlrev_b32_e32 v158, 16, v193
	v_and_b32_e32 v159, 0xffff0000, v193
	v_pk_mul_f32 v[106:107], v[106:107], v[160:161]
	v_pk_mul_f32 v[108:109], v[108:109], v[158:159]
	v_cvt_pk_bf16_f32 v106, v106, v107
	v_cvt_pk_bf16_f32 v107, v108, v109
	v_lshlrev_b32_e32 v108, 16, v101
	v_and_b32_e32 v109, 0xffff0000, v101
	v_lshlrev_b32_e32 v158, 16, v151
	v_and_b32_e32 v159, 0xffff0000, v151
	v_pk_mul_f32 v[108:109], v[154:155], v[108:109]
	v_pk_add_f32 v[154:155], v[0:1], v[156:157] op_sel_hi:[0,1]
	v_pk_mul_f32 v[154:155], v[154:155], v[158:159]
	v_cvt_pk_bf16_f32 v108, v108, v109
	v_cvt_pk_bf16_f32 v109, v154, v155
	s_nop 0
	v_permlane16_swap_b32_e32 v106, v108
	v_permlane16_swap_b32_e32 v107, v109
	global_store_dwordx4 v[110:111], v[106:109], off offset:-64
	v_pk_add_f32 v[102:103], v[0:1], v[102:103] op_sel_hi:[0,1]
	s_waitcnt vmcnt(1)
	v_mov_b32_e32 v101, v198
	s_nop 1
	v_permlane16_swap_b32_e32 v196, v101
	v_mov_b32_e32 v151, v199
	s_nop 1
	v_permlane16_swap_b32_e32 v197, v151
	v_lshlrev_b32_e32 v72, 16, v196
	v_and_b32_e32 v73, 0xffff0000, v196
	v_pk_add_f32 v[108:109], v[0:1], v[180:181] op_sel_hi:[0,1]
	v_lshlrev_b32_e32 v106, 16, v197
	v_and_b32_e32 v107, 0xffff0000, v197
	v_pk_mul_f32 v[72:73], v[108:109], v[72:73]
	v_pk_add_f32 v[108:109], v[0:1], v[182:183] op_sel_hi:[0,1]
	v_pk_mul_f32 v[108:109], v[108:109], v[106:107]
	v_cvt_pk_bf16_f32 v106, v72, v73
	v_lshlrev_b32_e32 v72, 16, v101
	v_and_b32_e32 v73, 0xffff0000, v101
	v_cvt_pk_bf16_f32 v107, v108, v109
	v_lshlrev_b32_e32 v108, 16, v151
	v_and_b32_e32 v109, 0xffff0000, v151
	v_pk_mul_f32 v[72:73], v[102:103], v[72:73]
	v_pk_add_f32 v[102:103], v[0:1], v[104:105] op_sel_hi:[0,1]
	v_pk_mul_f32 v[102:103], v[102:103], v[108:109]
	v_cvt_pk_bf16_f32 v108, v72, v73
	v_cvt_pk_bf16_f32 v109, v102, v103
	s_nop 0
	v_permlane16_swap_b32_e32 v106, v108
	v_permlane16_swap_b32_e32 v107, v109
	global_store_dwordx4 v[110:111], v[106:109], off
	s_cbranch_scc0 .LBB0_297
	s_and_b32 s1, s99, 31
	s_lshl_b32 s47, s1, 7
	s_cmp_eq_u32 s1, 0
	s_cselect_b64 s[10:11], -1, 0
	s_cmp_eq_u32 s1, 31
	v_cndmask_b32_e64 v0, v165, 0, s[10:11]
	v_sub_f32_e32 v0, v0, v113
	s_cselect_b64 vcc, -1, 0
	v_max_f32_e32 v153, 0xc3000000, v0
	v_cndmask_b32_e32 v0, v254, v168, vcc
	s_addk_i32 s47, 0xff80
	v_sub_f32_e32 v0, v0, v113
	s_add_u32 s0, s0, s36
	v_min_f32_e32 v154, 0x43000000, v0
	v_add_u32_e32 v0, s47, v127
	s_addc_u32 s1, 0, s37
	v_or_b32_e32 v2, s36, v0
	v_mov_b32_e32 v3, s37
	v_lshl_add_u64 v[4:5], s[0:1], 0, v[78:79]
	v_lshlrev_b64 v[2:3], 7, v[2:3]
	v_lshlrev_b64 v[6:7], 10, v[4:5]
	v_lshlrev_b64 v[4:5], 11, v[4:5]
	s_mov_b32 s28, 0
	v_cmp_gt_u32_e64 s[10:11], s38, v0
	v_lshl_add_u64 v[102:103], v[96:97], 0, v[6:7]
	v_lshl_add_u64 v[104:105], v[98:99], 0, v[4:5]
	s_mov_b64 s[12:13], -1
	v_lshlrev_b64 v[106:107], 1, v[2:3]
	s_barrier
